# merge epilogue: all gate loads of a half tile in flight together (one vmcnt wait per half instead of one per load)
# speedup vs baseline: 1.0189x; 1.0189x over previous
.LBB0_1034:
	v_mov_b32_e32 v0, v1
	s_lshl_b32 s2, s72, 8
	v_mbcnt_lo_u32_b32 v0, -1, v0
	v_readlane_b32 s3, v250, 1
	v_mbcnt_hi_u32_b32 v0, -1, v0
	s_add_i32 s2, s2, s3
	v_and_or_b32 v212, v0, 15, s2
	v_readlane_b32 s2, v254, 57
	v_readlane_b32 s3, v254, 58
	s_lshl_b32 s6, s71, 8
	s_ashr_i32 s7, s6, 31
	v_mov_b64_e32 v[130:131], s[2:3]
	s_movk_i32 s2, 0x1800
	v_mad_i64_i32 v[130:131], s[2:3], v212, s2, v[130:131]
	v_readlane_b32 s12, v254, 33
	v_readlane_b32 s13, v254, 34
	v_lshrrev_b32_e32 v0, 1, v0
	s_cmp_eq_u32 s70, 1
	s_movk_i32 s2, 0x800
	v_lshl_add_u64 v[130:131], s[6:7], 1, v[130:131]
	s_mov_b32 s13, s23
	v_and_b32_e32 v0, 24, v0
	s_cselect_b32 s2, 0x400, s2
	s_cmp_eq_u32 s70, 0
	v_lshl_add_u64 v[130:131], v[130:131], 0, s[12:13]
	v_lshlrev_b32_e32 v0, 1, v0
	s_movk_i32 s3, 0x1000
	s_cselect_b32 s2, 0, s2
	v_lshl_add_u64 v[130:131], v[130:131], 0, v[0:1]
	s_cselect_b32 s22, 0x800, s3
	s_lshl_b32 s2, s2, 1
	s_mov_b32 s3, s23
	v_lshl_add_u64 v[216:217], v[130:131], 0, s[2:3]
	global_load_dwordx4 v[190:193], v[216:217], off
	s_cmp_lt_i32 s70, 2
	s_cselect_b64 s[10:11], -1, 0
	s_cmp_gt_i32 s70, 1
	s_cselect_b64 s[8:9], -1, 0
	v_lshl_add_u64 v[214:215], v[130:131], 0, s[22:23]
	s_and_b64 vcc, exec, s[8:9]
	s_cbranch_vccnz .LBB0_1036
	global_load_dwordx4 v[186:189], v[214:215], off
.LBB0_1036:
	global_load_dwordx4 v[182:185], v[216:217], off offset:256
	v_cndmask_b32_e64 v130, 0, 1, s[10:11]
	v_cmp_ne_u32_e64 s[2:3], 1, v130
	s_andn2_b64 vcc, exec, s[10:11]
	s_cbranch_vccnz .LBB0_1038
	global_load_dwordx4 v[178:181], v[214:215], off offset:256
.LBB0_1038:
	v_add_co_u32_e32 v130, vcc, 0x18000, v216
	s_nop 1
	v_addc_co_u32_e32 v131, vcc, 0, v217, vcc
	global_load_dwordx4 v[174:177], v[130:131], off
	s_and_b64 vcc, exec, s[2:3]
	s_cbranch_vccnz .LBB0_1040
	v_add_co_u32_e32 v130, vcc, 0x18000, v214
	s_nop 1
	v_addc_co_u32_e32 v131, vcc, 0, v215, vcc
	global_load_dwordx4 v[170:173], v[130:131], off
.LBB0_1040:
	v_add_co_u32_e32 v130, vcc, 0x18000, v216
	s_nop 1
	v_addc_co_u32_e32 v131, vcc, 0, v217, vcc
	global_load_dwordx4 v[166:169], v[130:131], off offset:256
	s_and_b64 vcc, exec, s[2:3]
	s_cbranch_vccnz .LBB0_1042
	v_add_co_u32_e32 v130, vcc, 0x18000, v214
	s_nop 1
	v_addc_co_u32_e32 v131, vcc, 0, v215, vcc
	global_load_dwordx4 v[162:165], v[130:131], off offset:256
.LBB0_1042:
	v_add_co_u32_e32 v130, vcc, 0x30000, v216
	s_nop 1
	v_addc_co_u32_e32 v131, vcc, 0, v217, vcc
	global_load_dwordx4 v[158:161], v[130:131], off
	s_and_b64 vcc, exec, s[2:3]
	s_cbranch_vccnz .LBB0_1044
	v_add_co_u32_e32 v130, vcc, 0x30000, v214
	s_nop 1
	v_addc_co_u32_e32 v131, vcc, 0, v215, vcc
	global_load_dwordx4 v[154:157], v[130:131], off
.LBB0_1044:
	v_add_co_u32_e32 v130, vcc, 0x30000, v216
	s_nop 1
	v_addc_co_u32_e32 v131, vcc, 0, v217, vcc
	global_load_dwordx4 v[150:153], v[130:131], off offset:256
	s_and_b64 vcc, exec, s[2:3]
	s_cbranch_vccnz .LBB0_1046
	v_add_co_u32_e32 v130, vcc, 0x30000, v214
	s_nop 1
	v_addc_co_u32_e32 v131, vcc, 0, v215, vcc
	global_load_dwordx4 v[146:149], v[130:131], off offset:256
.LBB0_1046:
	v_add_co_u32_e32 v130, vcc, 0x48000, v216
	s_nop 1
	v_addc_co_u32_e32 v131, vcc, 0, v217, vcc
	global_load_dwordx4 v[142:145], v[130:131], off
	s_and_b64 vcc, exec, s[2:3]
	s_cbranch_vccnz .LBB0_1048
	v_add_co_u32_e32 v130, vcc, 0x48000, v214
	s_nop 1
	v_addc_co_u32_e32 v131, vcc, 0, v215, vcc
	global_load_dwordx4 v[138:141], v[130:131], off
.LBB0_1048:
	v_add_co_u32_e32 v130, vcc, 0x48000, v216
	s_nop 1
	v_addc_co_u32_e32 v131, vcc, 0, v217, vcc
	global_load_dwordx4 v[134:137], v[130:131], off offset:256
	s_and_b64 vcc, exec, s[2:3]
	s_cbranch_vccnz .LBB0_1050
	v_add_co_u32_e32 v130, vcc, 0x48000, v214
	s_nop 1
	v_addc_co_u32_e32 v131, vcc, 0, v215, vcc
	global_load_dwordx4 v[130:133], v[130:131], off offset:256
.LBB0_1050:
	s_waitcnt vmcnt(0)
	s_and_b64 vcc, exec, s[2:3]
	s_cbranch_vccz .Lmg_nocopy_0
	v_mov_b64_e32 v[186:187], v[190:191]
	v_mov_b64_e32 v[188:189], v[192:193]
	v_mov_b64_e32 v[178:179], v[182:183]
	v_mov_b64_e32 v[180:181], v[184:185]
	v_mov_b64_e32 v[170:171], v[174:175]
	v_mov_b64_e32 v[172:173], v[176:177]
	v_mov_b64_e32 v[162:163], v[166:167]
	v_mov_b64_e32 v[164:165], v[168:169]
	v_mov_b64_e32 v[154:155], v[158:159]
	v_mov_b64_e32 v[156:157], v[160:161]
	v_mov_b64_e32 v[146:147], v[150:151]
	v_mov_b64_e32 v[148:149], v[152:153]
	v_mov_b64_e32 v[138:139], v[142:143]
	v_mov_b64_e32 v[140:141], v[144:145]
	v_mov_b64_e32 v[130:131], v[134:135]
	v_mov_b64_e32 v[132:133], v[136:137]

.LBB0_1082:
	s_waitcnt vmcnt(0)
	v_add_co_u32_e32 v130, vcc, 0xc0000, v216
	s_nop 1
	v_addc_co_u32_e32 v131, vcc, 0, v217, vcc
	global_load_dwordx4 v[190:193], v[130:131], off
	s_and_b64 vcc, exec, s[2:3]
	s_cbranch_vccnz .LBB0_1084
	v_add_co_u32_e32 v130, vcc, 0xc0000, v214
	s_nop 1
	v_addc_co_u32_e32 v131, vcc, 0, v215, vcc
	global_load_dwordx4 v[186:189], v[130:131], off
.LBB0_1084:
	v_add_co_u32_e32 v130, vcc, 0xc0000, v216
	s_nop 1
	v_addc_co_u32_e32 v131, vcc, 0, v217, vcc
	global_load_dwordx4 v[182:185], v[130:131], off offset:256
	s_and_b64 vcc, exec, s[2:3]
	s_cbranch_vccnz .LBB0_1086
	v_add_co_u32_e32 v130, vcc, 0xc0000, v214
	s_nop 1
	v_addc_co_u32_e32 v131, vcc, 0, v215, vcc
	global_load_dwordx4 v[178:181], v[130:131], off offset:256
.LBB0_1086:
	v_add_co_u32_e32 v130, vcc, 0xd8000, v216
	s_nop 1
	v_addc_co_u32_e32 v131, vcc, 0, v217, vcc
	global_load_dwordx4 v[174:177], v[130:131], off
	s_and_b64 vcc, exec, s[2:3]
	s_cbranch_vccnz .LBB0_1088
	v_add_co_u32_e32 v130, vcc, 0xd8000, v214
	s_nop 1
	v_addc_co_u32_e32 v131, vcc, 0, v215, vcc
	global_load_dwordx4 v[170:173], v[130:131], off
.LBB0_1088:
	v_add_co_u32_e32 v130, vcc, 0xd8000, v216
	s_nop 1
	v_addc_co_u32_e32 v131, vcc, 0, v217, vcc
	global_load_dwordx4 v[166:169], v[130:131], off offset:256
	s_and_b64 vcc, exec, s[2:3]
	s_cbranch_vccnz .LBB0_1090
	v_add_co_u32_e32 v130, vcc, 0xd8000, v214
	s_nop 1
	v_addc_co_u32_e32 v131, vcc, 0, v215, vcc
	global_load_dwordx4 v[162:165], v[130:131], off offset:256
.LBB0_1090:
	v_add_co_u32_e32 v130, vcc, 0xf0000, v216
	s_nop 1
	v_addc_co_u32_e32 v131, vcc, 0, v217, vcc
	global_load_dwordx4 v[158:161], v[130:131], off
	s_and_b64 vcc, exec, s[2:3]
	s_cbranch_vccnz .LBB0_1092
	v_add_co_u32_e32 v130, vcc, 0xf0000, v214
	s_nop 1
	v_addc_co_u32_e32 v131, vcc, 0, v215, vcc
	global_load_dwordx4 v[154:157], v[130:131], off
.LBB0_1092:
	v_add_co_u32_e32 v130, vcc, 0xf0000, v216
	s_nop 1
	v_addc_co_u32_e32 v131, vcc, 0, v217, vcc
	global_load_dwordx4 v[150:153], v[130:131], off offset:256
	s_and_b64 vcc, exec, s[2:3]
	s_cbranch_vccnz .LBB0_1094
	v_add_co_u32_e32 v130, vcc, 0xf0000, v214
	s_nop 1
	v_addc_co_u32_e32 v131, vcc, 0, v215, vcc
	global_load_dwordx4 v[146:149], v[130:131], off offset:256
.LBB0_1094:
	v_add_co_u32_e32 v130, vcc, 0x108000, v216
	s_nop 1
	v_addc_co_u32_e32 v131, vcc, 0, v217, vcc
	global_load_dwordx4 v[142:145], v[130:131], off
	s_and_b64 vcc, exec, s[2:3]
	s_cbranch_vccnz .LBB0_1096
	v_add_co_u32_e32 v130, vcc, 0x108000, v214
	s_nop 1
	v_addc_co_u32_e32 v131, vcc, 0, v215, vcc
	global_load_dwordx4 v[138:141], v[130:131], off
.LBB0_1096:
	v_add_co_u32_e32 v130, vcc, 0x108000, v216
	s_nop 1
	v_addc_co_u32_e32 v131, vcc, 0, v217, vcc
	global_load_dwordx4 v[134:137], v[130:131], off offset:256
	s_and_b64 vcc, exec, s[2:3]
	s_cbranch_vccnz .LBB0_1098
	v_add_co_u32_e32 v130, vcc, 0x108000, v214
	s_nop 1
	v_addc_co_u32_e32 v131, vcc, 0, v215, vcc
	global_load_dwordx4 v[130:133], v[130:131], off offset:256
